# in-projection GEMM K-loop: LDS-DMA loads switched to saddr + 32-bit voffset form (no per-load 64-bit VALU add in the loader wave)
# speedup vs baseline: 1.0073x; 1.0073x over previous
; #define PG8_STAGE(bufoff, gbase, voff) do { _Pragma("unroll") for (int _i = 0; _i < 2; ++_i) \
;         __builtin_amdgcn_global_load_lds((const unsigned*)((const char*)(gbase) + (voff)[_i]), (LAS unsigned*)(lds + (bufoff) + ldsw + _i * 8192), 16, 0, 0); } while (0)
; #define PG8_LDA(dst, b, h) do { _Pragma("unroll") for (int m = 0; m < 4; ++m) _Pragma("unroll") for (int k = 0; k < 2; ++k) dst[m][k] = *(const LAS bf16x8*)(lds + PG8_SA(b, h) + aoff + m * 2048 + k * 1024); } while (0)
; #define PG8_LDB(dst, b, h) do { _Pragma("unroll") for (int n = 0; n < 2; ++n) _Pragma("unroll") for (int k = 0; k < 2; ++k) dst[n][k] = *(const LAS bf16x8*)(lds + PG8_SB(b, h) + boff + n * 2048 + k * 1024); } while (0)
; #define PG8_MMA(ai, bj, At, Bt) do { __builtin_amdgcn_s_setprio(1); _Pragma("unroll") for (int m = 0; m < 4; ++m) _Pragma("unroll") for (int n = 0; n < 2; ++n) _Pragma("unroll") for (int k = 0; k < 2; ++k) \
;         acc[ai][bj][m][n] = __builtin_amdgcn_mfma_f32_16x16x32_bf16(Bt[n][k], At[m][k], acc[ai][bj][m][n], 0, 0, 0); __builtin_amdgcn_s_setprio(0); } while (0)
; template <class Epi, class Sched, bool ALIGN_EPI = false, bool SP2 = false, bool TWOA = false, bool AGM = false>
; __device__ __forceinline__ void gemm_phase(LAS unsigned char* lds, const Gemm g, const Sched& S, const Epi& E, int wid) {
;     ...
;             if constexpr (SP2) {
;             PG8_LDB(B0, 0, 0); PG8_LDB(B1, 0, 1); PG8_SCHED; PG8_LDA(At, 0, 0); PG8_STAGE(PG8_SA(1, 1), a1 + hstepA, voffA);
;             PG8_WAIT_V(8); PG8_WAIT_L(0); PG8_BAR; PG8_MMA(0, 0, At, B0); PG8_MMA(0, 1, At, B1); PG8_BAR; PG8_SCHED;
;             PG8_LDA(At, 0, 1); PG8_STAGE(PG8_SB(0, 0), b2, voffB); PG8_STAGE(PG8_SB(0, 1), b2 + hstep, voffB); PG8_STAGE(PG8_SA(0, 0), a2, voffA);
;             PG8_WAIT_V(8); PG8_WAIT_L(0); PG8_BAR; PG8_MMA(1, 0, At, B0); PG8_MMA(1, 1, At, B1); PG8_BAR; PG8_SCHED;
;             PG8_LDB(B0, 1, 0); PG8_LDB(B1, 1, 1); PG8_SCHED; PG8_LDA(At, 1, 0); PG8_STAGE(PG8_SA(0, 1), a2 + hstepA, voffA);
;             PG8_WAIT_V(8); PG8_WAIT_L(0); PG8_BAR; PG8_MMA(0, 0, At, B0); PG8_MMA(0, 1, At, B1); PG8_BAR; PG8_SCHED;
;             PG8_LDA(At, 1, 1); PG8_STAGE(PG8_SB(1, 0), b3, voffB); PG8_STAGE(PG8_SB(1, 1), b3 + hstep, voffB); PG8_STAGE(PG8_SA(1, 0), a3, voffA);
;             PG8_WAIT_V(8); PG8_WAIT_L(0); PG8_BAR; PG8_MMA(1, 0, At, B0); PG8_MMA(1, 1, At, B1); PG8_BAR; PG8_SCHED;
.LBB0_230:
	ds_read_b128 v[146:149], v155
	ds_read_b128 v[160:163], v155 offset:1024
	ds_read_b128 v[164:167], v155 offset:2048
	ds_read_b128 v[168:171], v155 offset:3072
	ds_read_b128 v[172:175], v156
	ds_read_b128 v[176:179], v156 offset:1024
	ds_read_b128 v[180:183], v156 offset:2048
	ds_read_b128 v[184:187], v156 offset:3072
	s_add_u32 s12, s10, 0xfff00080
	s_addc_u32 s13, s11, -1
	s_cmp_eq_u32 s70, 60
	s_cselect_b32 s67, s7, s13
	s_cselect_b32 s66, s9, s12
	s_cselect_b32 s13, s53, s69
	s_cselect_b32 s12, s55, s68
	s_add_i32 m0, s76, 0xc000
	ds_read_b128 v[188:191], v157
	ds_read_b128 v[192:195], v157 offset:1024
	ds_read_b128 v[196:199], v157 offset:2048
	ds_read_b128 v[200:203], v157 offset:3072
	ds_read_b128 v[204:207], v157 offset:4096
	ds_read_b128 v[208:211], v157 offset:5120
	ds_read_b128 v[212:215], v157 offset:6144
	ds_read_b128 v[216:219], v157 offset:7168
	global_load_lds_dwordx4 v138, s[10:11]
	s_add_i32 m0, s76, 0xe000
	s_nop 0
	global_load_lds_dwordx4 v140, s[10:11]
	s_waitcnt vmcnt(8)
	s_waitcnt lgkmcnt(0)
	s_barrier
	s_setprio 1
	s_waitcnt lgkmcnt(0)
	v_mfma_f32_16x16x32_bf16 v[124:127], v[146:149], v[188:191], v[124:127]
	v_mfma_f32_16x16x32_bf16 v[120:123], v[164:167], v[188:191], v[120:123]
	v_mfma_f32_16x16x32_bf16 v[108:111], v[146:149], v[196:199], v[108:111]
	v_mfma_f32_16x16x32_bf16 v[104:107], v[164:167], v[196:199], v[104:107]
	v_mfma_f32_16x16x32_bf16 v[92:95], v[146:149], v[204:207], v[92:95]
	v_mfma_f32_16x16x32_bf16 v[88:91], v[164:167], v[204:207], v[88:91]
	v_mfma_f32_16x16x32_bf16 v[76:79], v[146:149], v[212:215], v[76:79]
	v_mfma_f32_16x16x32_bf16 v[72:75], v[164:167], v[212:215], v[72:75]
	v_mfma_f32_16x16x32_bf16 v[124:127], v[160:163], v[192:195], v[124:127]
	v_mfma_f32_16x16x32_bf16 v[120:123], v[168:171], v[192:195], v[120:123]
	v_mfma_f32_16x16x32_bf16 v[108:111], v[160:163], v[200:203], v[108:111]
	v_mfma_f32_16x16x32_bf16 v[104:107], v[168:171], v[200:203], v[104:107]
	v_mfma_f32_16x16x32_bf16 v[92:95], v[160:163], v[208:211], v[92:95]
	v_mfma_f32_16x16x32_bf16 v[88:91], v[168:171], v[208:211], v[88:91]
	v_mfma_f32_16x16x32_bf16 v[76:79], v[160:163], v[216:219], v[76:79]
	v_mfma_f32_16x16x32_bf16 v[72:75], v[168:171], v[216:219], v[72:75]
	s_setprio 0
	s_setprio 1
	v_mfma_f32_16x16x32_bf16 v[116:119], v[172:175], v[188:191], v[116:119]
	v_mfma_f32_16x16x32_bf16 v[112:115], v[180:183], v[188:191], v[112:115]
	v_mfma_f32_16x16x32_bf16 v[100:103], v[172:175], v[196:199], v[100:103]
	v_mfma_f32_16x16x32_bf16 v[96:99], v[180:183], v[196:199], v[96:99]
	v_mfma_f32_16x16x32_bf16 v[84:87], v[172:175], v[204:207], v[84:87]
	v_mfma_f32_16x16x32_bf16 v[80:83], v[180:183], v[204:207], v[80:83]
	v_mfma_f32_16x16x32_bf16 v[68:71], v[172:175], v[212:215], v[68:71]
	v_mfma_f32_16x16x32_bf16 v[64:67], v[180:183], v[212:215], v[64:67]
	v_mfma_f32_16x16x32_bf16 v[116:119], v[176:179], v[192:195], v[116:119]
	v_mfma_f32_16x16x32_bf16 v[112:115], v[184:187], v[192:195], v[112:115]
	v_mfma_f32_16x16x32_bf16 v[100:103], v[176:179], v[200:203], v[100:103]
	v_mfma_f32_16x16x32_bf16 v[96:99], v[184:187], v[200:203], v[96:99]
	v_mfma_f32_16x16x32_bf16 v[84:87], v[176:179], v[208:211], v[84:87]
	v_mfma_f32_16x16x32_bf16 v[80:83], v[184:187], v[208:211], v[80:83]
	v_mfma_f32_16x16x32_bf16 v[68:71], v[176:179], v[216:219], v[68:71]
	v_mfma_f32_16x16x32_bf16 v[64:67], v[184:187], v[216:219], v[64:67]
	s_setprio 0
	s_barrier
	s_add_i32 s34, s95, s75
	s_mov_b32 m0, s34
	ds_read_b128 v[188:191], v157 offset:16384
	ds_read_b128 v[192:195], v157 offset:17408
	ds_read_b128 v[196:199], v157 offset:18432
	ds_read_b128 v[200:203], v157 offset:19456
	ds_read_b128 v[204:207], v157 offset:20480
	ds_read_b128 v[208:211], v157 offset:21504
	ds_read_b128 v[212:215], v157 offset:22528
	ds_read_b128 v[216:219], v157 offset:23552
	global_load_lds_dwordx4 v130, s[12:13]
	s_add_i32 m0, s34, 0x2000
	s_add_u32 s34, s12, 0x100000
	s_addc_u32 s35, s13, 0
	s_add_i32 s71, s96, s75
	global_load_lds_dwordx4 v134, s[12:13]
	s_mov_b32 m0, s71
	s_nop 0
	global_load_lds_dwordx4 v130, s[34:35]
	s_add_i32 m0, s71, 0x2000
	s_nop 0
	global_load_lds_dwordx4 v134, s[34:35]
	s_mov_b32 m0, s76
	s_nop 0
	global_load_lds_dwordx4 v128, s[66:67]
	s_mov_b32 m0, s77
	s_nop 0
	global_load_lds_dwordx4 v132, s[66:67]
	s_waitcnt vmcnt(8)
	s_waitcnt lgkmcnt(0)
	s_barrier
	s_setprio 1
	s_waitcnt lgkmcnt(0)
	v_mfma_f32_16x16x32_bf16 v[60:63], v[146:149], v[188:191], v[60:63]
	v_mfma_f32_16x16x32_bf16 v[56:59], v[164:167], v[188:191], v[56:59]
	v_mfma_f32_16x16x32_bf16 v[44:47], v[146:149], v[196:199], v[44:47]
	v_mfma_f32_16x16x32_bf16 v[40:43], v[164:167], v[196:199], v[40:43]
	v_mfma_f32_16x16x32_bf16 v[28:31], v[146:149], v[204:207], v[28:31]
	v_mfma_f32_16x16x32_bf16 v[24:27], v[164:167], v[204:207], v[24:27]
	v_mfma_f32_16x16x32_bf16 v[12:15], v[146:149], v[212:215], v[12:15]
	v_mfma_f32_16x16x32_bf16 v[8:11], v[164:167], v[212:215], v[8:11]
	v_mfma_f32_16x16x32_bf16 v[60:63], v[160:163], v[192:195], v[60:63]
	v_mfma_f32_16x16x32_bf16 v[56:59], v[168:171], v[192:195], v[56:59]
	v_mfma_f32_16x16x32_bf16 v[44:47], v[160:163], v[200:203], v[44:47]
	v_mfma_f32_16x16x32_bf16 v[40:43], v[168:171], v[200:203], v[40:43]
	v_mfma_f32_16x16x32_bf16 v[28:31], v[160:163], v[208:211], v[28:31]
	v_mfma_f32_16x16x32_bf16 v[24:27], v[168:171], v[208:211], v[24:27]
	v_mfma_f32_16x16x32_bf16 v[12:15], v[160:163], v[216:219], v[12:15]
	v_mfma_f32_16x16x32_bf16 v[8:11], v[168:171], v[216:219], v[8:11]
	s_setprio 0
	s_setprio 1
	v_mfma_f32_16x16x32_bf16 v[52:55], v[172:175], v[188:191], v[52:55]
	v_mfma_f32_16x16x32_bf16 v[48:51], v[180:183], v[188:191], v[48:51]
	v_mfma_f32_16x16x32_bf16 v[36:39], v[172:175], v[196:199], v[36:39]
	v_mfma_f32_16x16x32_bf16 v[32:35], v[180:183], v[196:199], v[32:35]
	v_mfma_f32_16x16x32_bf16 v[20:23], v[172:175], v[204:207], v[20:23]
	v_mfma_f32_16x16x32_bf16 v[16:19], v[180:183], v[204:207], v[16:19]
	v_mfma_f32_16x16x32_bf16 v[4:7], v[172:175], v[212:215], v[4:7]
	v_mfma_f32_16x16x32_bf16 v[0:3], v[180:183], v[212:215], v[0:3]
	v_mfma_f32_16x16x32_bf16 v[52:55], v[176:179], v[192:195], v[52:55]
	v_mfma_f32_16x16x32_bf16 v[48:51], v[184:187], v[192:195], v[48:51]
	v_mfma_f32_16x16x32_bf16 v[36:39], v[176:179], v[200:203], v[36:39]
	v_mfma_f32_16x16x32_bf16 v[32:35], v[184:187], v[200:203], v[32:35]
	v_mfma_f32_16x16x32_bf16 v[20:23], v[176:179], v[208:211], v[20:23]
	v_mfma_f32_16x16x32_bf16 v[16:19], v[184:187], v[208:211], v[16:19]
	v_mfma_f32_16x16x32_bf16 v[4:7], v[176:179], v[216:219], v[4:7]
	v_mfma_f32_16x16x32_bf16 v[0:3], v[184:187], v[216:219], v[0:3]
	s_setprio 0
	s_barrier
; #define PG8_STAGE(bufoff, gbase, voff) do { _Pragma("unroll") for (int _i = 0; _i < 2; ++_i) \
;         __builtin_amdgcn_global_load_lds((const unsigned*)((const char*)(gbase) + (voff)[_i]), (LAS unsigned*)(lds + (bufoff) + ldsw + _i * 8192), 16, 0, 0); } while (0)
; #define PG8_LDA(dst, b, h) do { _Pragma("unroll") for (int m = 0; m < 4; ++m) _Pragma("unroll") for (int k = 0; k < 2; ++k) dst[m][k] = *(const LAS bf16x8*)(lds + PG8_SA(b, h) + aoff + m * 2048 + k * 1024); } while (0)
; #define PG8_LDB(dst, b, h) do { _Pragma("unroll") for (int n = 0; n < 2; ++n) _Pragma("unroll") for (int k = 0; k < 2; ++k) dst[n][k] = *(const LAS bf16x8*)(lds + PG8_SB(b, h) + boff + n * 2048 + k * 1024); } while (0)
; #define PG8_MMA(ai, bj, At, Bt) do { __builtin_amdgcn_s_setprio(1); _Pragma("unroll") for (int m = 0; m < 4; ++m) _Pragma("unroll") for (int n = 0; n < 2; ++n) _Pragma("unroll") for (int k = 0; k < 2; ++k) \
;         acc[ai][bj][m][n] = __builtin_amdgcn_mfma_f32_16x16x32_bf16(Bt[n][k], At[m][k], acc[ai][bj][m][n], 0, 0, 0); __builtin_amdgcn_s_setprio(0); } while (0)
; #define PG8_WAIT_V(n) asm volatile("s_waitcnt vmcnt(" #n ")" ::: "memory")
; #define PG8_WAIT_L(n) asm volatile("s_waitcnt lgkmcnt(" #n ")" ::: "memory")
; #define PG8_BAR __builtin_amdgcn_s_barrier()
; #define PG8_SCHED __builtin_amdgcn_sched_barrier(0)
; template <class Epi, class Sched, bool ALIGN_EPI = false, bool SP2 = false, bool TWOA = false, bool AGM = false>
; __device__ __forceinline__ void gemm_phase(LAS unsigned char* lds, const Gemm g, const Sched& S, const Epi& E, int wid) {
;     ...
;             PG8_LDB(B0, 1, 0); PG8_LDB(B1, 1, 1); PG8_SCHED; PG8_LDA(At, 1, 0); PG8_STAGE(PG8_SA(0, 1), a2 + hstepA, voffA);
;             PG8_WAIT_V(8); PG8_WAIT_L(0); PG8_BAR; PG8_MMA(0, 0, At, B0); PG8_MMA(0, 1, At, B1); PG8_BAR; PG8_SCHED;
;             PG8_LDA(At, 1, 1); PG8_STAGE(PG8_SB(1, 0), b3, voffB); PG8_STAGE(PG8_SB(1, 1), b3 + hstep, voffB); PG8_STAGE(PG8_SA(1, 0), a3, voffA);
;             PG8_WAIT_V(8); PG8_WAIT_L(0); PG8_BAR; PG8_MMA(1, 0, At, B0); PG8_MMA(1, 1, At, B1); PG8_BAR; PG8_SCHED;
	s_add_i32 s71, 0, 0x18000
	v_add_u32_e32 v136, s71, v153
	s_add_i32 s72, 0, 0x1c000
	ds_read_b128 v[146:149], v136
	ds_read_b128 v[160:163], v136 offset:1024
	ds_read_b128 v[164:167], v136 offset:2048
	ds_read_b128 v[168:171], v136 offset:3072
	v_add_u32_e32 v136, s72, v153
	ds_read_b128 v[172:175], v136
	ds_read_b128 v[176:179], v136 offset:1024
	ds_read_b128 v[180:183], v136 offset:2048
	ds_read_b128 v[184:187], v136 offset:3072
	s_add_u32 s34, s66, 0x100000
	s_addc_u32 s35, s67, 0
	s_mov_b32 m0, s81
	ds_read_b128 v[188:191], v157 offset:32768
	ds_read_b128 v[192:195], v157 offset:33792
	ds_read_b128 v[196:199], v157 offset:34816
	ds_read_b128 v[200:203], v157 offset:35840
	ds_read_b128 v[204:207], v157 offset:36864
	ds_read_b128 v[208:211], v157 offset:37888
	ds_read_b128 v[212:215], v157 offset:38912
	ds_read_b128 v[216:219], v157 offset:39936
	global_load_lds_dwordx4 v128, s[34:35]
	s_mov_b32 m0, s82
	s_nop 0
	global_load_lds_dwordx4 v132, s[34:35]
	s_waitcnt vmcnt(8)
	s_waitcnt lgkmcnt(0)
	s_barrier
	s_setprio 1
	s_waitcnt lgkmcnt(0)
	v_mfma_f32_16x16x32_bf16 v[124:127], v[146:149], v[188:191], v[124:127]
	v_mfma_f32_16x16x32_bf16 v[120:123], v[164:167], v[188:191], v[120:123]
	v_mfma_f32_16x16x32_bf16 v[108:111], v[146:149], v[196:199], v[108:111]
	v_mfma_f32_16x16x32_bf16 v[104:107], v[164:167], v[196:199], v[104:107]
	v_mfma_f32_16x16x32_bf16 v[92:95], v[146:149], v[204:207], v[92:95]
	v_mfma_f32_16x16x32_bf16 v[88:91], v[164:167], v[204:207], v[88:91]
	v_mfma_f32_16x16x32_bf16 v[76:79], v[146:149], v[212:215], v[76:79]
	v_mfma_f32_16x16x32_bf16 v[72:75], v[164:167], v[212:215], v[72:75]
	v_mfma_f32_16x16x32_bf16 v[124:127], v[160:163], v[192:195], v[124:127]
	v_mfma_f32_16x16x32_bf16 v[120:123], v[168:171], v[192:195], v[120:123]
	v_mfma_f32_16x16x32_bf16 v[108:111], v[160:163], v[200:203], v[108:111]
	v_mfma_f32_16x16x32_bf16 v[104:107], v[168:171], v[200:203], v[104:107]
	v_mfma_f32_16x16x32_bf16 v[92:95], v[160:163], v[208:211], v[92:95]
	v_mfma_f32_16x16x32_bf16 v[88:91], v[168:171], v[208:211], v[88:91]
	v_mfma_f32_16x16x32_bf16 v[76:79], v[160:163], v[216:219], v[76:79]
	v_mfma_f32_16x16x32_bf16 v[72:75], v[168:171], v[216:219], v[72:75]
	s_setprio 0
	s_setprio 1
	v_mfma_f32_16x16x32_bf16 v[116:119], v[172:175], v[188:191], v[116:119]
	v_mfma_f32_16x16x32_bf16 v[112:115], v[180:183], v[188:191], v[112:115]
	v_mfma_f32_16x16x32_bf16 v[100:103], v[172:175], v[196:199], v[100:103]
	v_mfma_f32_16x16x32_bf16 v[96:99], v[180:183], v[196:199], v[96:99]
	v_mfma_f32_16x16x32_bf16 v[84:87], v[172:175], v[204:207], v[84:87]
	v_mfma_f32_16x16x32_bf16 v[80:83], v[180:183], v[204:207], v[80:83]
	v_mfma_f32_16x16x32_bf16 v[68:71], v[172:175], v[212:215], v[68:71]
	v_mfma_f32_16x16x32_bf16 v[64:67], v[180:183], v[212:215], v[64:67]
	v_mfma_f32_16x16x32_bf16 v[116:119], v[176:179], v[192:195], v[116:119]
	v_mfma_f32_16x16x32_bf16 v[112:115], v[184:187], v[192:195], v[112:115]
	v_mfma_f32_16x16x32_bf16 v[100:103], v[176:179], v[200:203], v[100:103]
	v_mfma_f32_16x16x32_bf16 v[96:99], v[184:187], v[200:203], v[96:99]
	v_mfma_f32_16x16x32_bf16 v[84:87], v[176:179], v[208:211], v[84:87]
	v_mfma_f32_16x16x32_bf16 v[80:83], v[184:187], v[208:211], v[80:83]
	v_mfma_f32_16x16x32_bf16 v[68:71], v[176:179], v[216:219], v[68:71]
	v_mfma_f32_16x16x32_bf16 v[64:67], v[184:187], v[216:219], v[64:67]
	s_setprio 0
	s_barrier
	s_add_i32 s34, s71, s75
	s_add_u32 s98, s12, s46
	s_addc_u32 s99, s13, s47
	s_mov_b32 m0, s34
	ds_read_b128 v[188:191], v157 offset:49152
	ds_read_b128 v[192:195], v157 offset:50176
	ds_read_b128 v[196:199], v157 offset:51200
	ds_read_b128 v[200:203], v157 offset:52224
	ds_read_b128 v[204:207], v157 offset:53248
	ds_read_b128 v[208:211], v157 offset:54272
	ds_read_b128 v[212:215], v157 offset:55296
	ds_read_b128 v[216:219], v157 offset:56320
	global_load_lds_dwordx4 v130, s[98:99]
	s_add_i32 m0, s34, 0x2000
	s_add_u32 s12, s12, 0x100080
	s_addc_u32 s13, s13, 0
	s_add_i32 s34, s72, s75
	global_load_lds_dwordx4 v134, s[98:99]
	s_mov_b32 m0, s34
	s_nop 0
	global_load_lds_dwordx4 v130, s[12:13]
	s_add_i32 m0, s34, 0x2000
	s_nop 0
	global_load_lds_dwordx4 v134, s[12:13]
	s_add_u32 s100, s66, s46
	s_addc_u32 s101, s67, s47
	s_mov_b32 m0, s88
	s_nop 0
	global_load_lds_dwordx4 v128, s[100:101]
	s_mov_b32 m0, s89
	s_nop 0
	global_load_lds_dwordx4 v132, s[100:101]
	s_waitcnt vmcnt(8)
	s_waitcnt lgkmcnt(0)
	s_barrier
	s_setprio 1
	s_waitcnt lgkmcnt(0)
	v_mfma_f32_16x16x32_bf16 v[60:63], v[146:149], v[188:191], v[60:63]
	v_mfma_f32_16x16x32_bf16 v[56:59], v[164:167], v[188:191], v[56:59]
	v_mfma_f32_16x16x32_bf16 v[44:47], v[146:149], v[196:199], v[44:47]
	v_mfma_f32_16x16x32_bf16 v[40:43], v[164:167], v[196:199], v[40:43]
	v_mfma_f32_16x16x32_bf16 v[28:31], v[146:149], v[204:207], v[28:31]
	v_mfma_f32_16x16x32_bf16 v[24:27], v[164:167], v[204:207], v[24:27]
	v_mfma_f32_16x16x32_bf16 v[12:15], v[146:149], v[212:215], v[12:15]
	v_mfma_f32_16x16x32_bf16 v[8:11], v[164:167], v[212:215], v[8:11]
	v_mfma_f32_16x16x32_bf16 v[60:63], v[160:163], v[192:195], v[60:63]
	v_mfma_f32_16x16x32_bf16 v[56:59], v[168:171], v[192:195], v[56:59]
	v_mfma_f32_16x16x32_bf16 v[44:47], v[160:163], v[200:203], v[44:47]
	v_mfma_f32_16x16x32_bf16 v[40:43], v[168:171], v[200:203], v[40:43]
	v_mfma_f32_16x16x32_bf16 v[28:31], v[160:163], v[208:211], v[28:31]
	v_mfma_f32_16x16x32_bf16 v[24:27], v[168:171], v[208:211], v[24:27]
	v_mfma_f32_16x16x32_bf16 v[12:15], v[160:163], v[216:219], v[12:15]
	v_mfma_f32_16x16x32_bf16 v[8:11], v[168:171], v[216:219], v[8:11]
	s_setprio 0
	s_setprio 1
	v_mfma_f32_16x16x32_bf16 v[52:55], v[172:175], v[188:191], v[52:55]
	v_mfma_f32_16x16x32_bf16 v[48:51], v[180:183], v[188:191], v[48:51]
	v_mfma_f32_16x16x32_bf16 v[36:39], v[172:175], v[196:199], v[36:39]
	v_mfma_f32_16x16x32_bf16 v[32:35], v[180:183], v[196:199], v[32:35]
	v_mfma_f32_16x16x32_bf16 v[20:23], v[172:175], v[204:207], v[20:23]
	v_mfma_f32_16x16x32_bf16 v[16:19], v[180:183], v[204:207], v[16:19]
	v_mfma_f32_16x16x32_bf16 v[4:7], v[172:175], v[212:215], v[4:7]
	v_mfma_f32_16x16x32_bf16 v[0:3], v[180:183], v[212:215], v[0:3]
	v_mfma_f32_16x16x32_bf16 v[52:55], v[176:179], v[192:195], v[52:55]
	v_mfma_f32_16x16x32_bf16 v[48:51], v[184:187], v[192:195], v[48:51]
	v_mfma_f32_16x16x32_bf16 v[36:39], v[176:179], v[200:203], v[36:39]
	v_mfma_f32_16x16x32_bf16 v[32:35], v[184:187], v[200:203], v[32:35]
	v_mfma_f32_16x16x32_bf16 v[20:23], v[176:179], v[208:211], v[20:23]
	v_mfma_f32_16x16x32_bf16 v[16:19], v[184:187], v[208:211], v[16:19]
	v_mfma_f32_16x16x32_bf16 v[4:7], v[176:179], v[216:219], v[4:7]
	v_mfma_f32_16x16x32_bf16 v[0:3], v[184:187], v[216:219], v[0:3]
	s_setprio 0
	s_barrier
	s_add_i32 s70, s70, 2
	s_add_u32 s10, s10, 0x100
	s_addc_u32 s11, s11, 0
	s_add_u32 s68, s68, 0x100
	s_addc_u32 s69, s69, 0
	s_cmp_gt_u32 s70, 61
	s_cbranch_scc0 .LBB0_230
	s_and_b64 vcc, exec, s[50:51]
	s_cbranch_vccz .LBB0_233
	s_barrier
